# LayerNorm row loops: next row loaded into spare VGPRs while the current row is normalised (register double-buffering), on top of the DPP reductions
# speedup vs baseline: 1.0033x; 1.0033x over previous
; DI float lo2f(unsigned v) { return __uint_as_float(v << 16); }
; DI float hi2f(unsigned v) { return __uint_as_float(v & 0xffff0000u); }
; DI float wave_sum(float v) { for (int o = 32; o >= 1; o >>= 1) v += __shfl_xor(v, o); return v; }
; DI void ln_phase(int wvs, bf16_t* HB, const float* __restrict__ g, const float* __restrict__ bta, float* fout, bool dostore = true) {
;   const int tid = opaque_tid(wvs);
;   const int lane = tid & 63, w = tid >> 6;
;   for (int row = blockIdx.x * 8 + w; row < MTOT; row += gridDim.x * 8) {
;     bf16_t* p = HB + (size_t)row * 1024;
;     float v[16];
;     float s = 0.f;
; #pragma unroll
;     for (int i = 0; i < 2; ++i) {
;       const u32x4 raw = *(const u32x4*)(p + i * 512 + lane * 8);
; #pragma unroll
;       for (int j = 0; j < 4; ++j) { v[i * 8 + 2 * j] = lo2f(raw[j]); v[i * 8 + 2 * j + 1] = hi2f(raw[j]); }
;     }
; #pragma unroll
;     for (int i = 0; i < 16; ++i) s += v[i];
;     const float mean = wave_sum(s) * (1.f / 1024.f);
;     float q = 0.f;
; #pragma unroll
;     for (int i = 0; i < 16; ++i) { v[i] -= mean; q += v[i] * v[i]; }
;     const float rstd = rsqrtf(wave_sum(q) * (1.f / 1024.f) + 1e-5f);
; #pragma unroll
;     for (int i = 0; i < 2; ++i) {
;       const int c = i * 512 + lane * 8;
;       const float4 g0 = *(const float4*)(g + c), g1 = *(const float4*)(g + c + 4), b0 = *(const float4*)(bta + c), b1 = *(const float4*)(bta + c + 4);
.LBB0_497:
	v_readlane_b32 s6, v251, 2
	v_mbcnt_lo_u32_b32 v0, -1, 0
	v_mbcnt_hi_u32_b32 v0, -1, v0
	s_nop 1
	v_or_b32_e32 v1, s6, v0
	v_ashrrev_i32_e32 v1, 6, v1
	v_readlane_b32 s6, v251, 37
	s_nop 1
	v_add_u32_e32 v32, s6, v1
	s_mov_b32 s6, 0x8000
	v_cmp_gt_i32_e32 vcc, s6, v32
	s_and_saveexec_b64 s[40:41], vcc
	s_cbranch_execz .LBB0_500
	v_readlane_b32 s44, v254, 41
	v_lshlrev_b32_e32 v0, 3, v0
	v_readlane_b32 s45, v254, 42
	v_readlane_b32 s46, v254, 43
	v_readlane_b32 s47, v254, 44
	v_and_b32_e32 v33, 0x1f8, v0
	v_readlane_b32 s44, v253, 15
	v_lshlrev_b32_e32 v28, 2, v33
	v_readlane_b32 s58, v254, 55
	v_readlane_b32 s59, v254, 56
	v_readlane_b32 s45, v253, 16
	s_nop 3
	global_load_dwordx4 v[0:3], v28, s[58:59] offset:16
	global_load_dwordx4 v[4:7], v28, s[58:59]
	global_load_dwordx4 v[8:11], v28, s[44:45] offset:16
	global_load_dwordx4 v[12:15], v28, s[44:45]
	global_load_dwordx4 v[16:19], v28, s[58:59] offset:2064
	global_load_dwordx4 v[20:23], v28, s[58:59] offset:2048
	global_load_dwordx4 v[24:27], v28, s[44:45] offset:2064
	s_nop 0
	global_load_dwordx4 v[28:31], v28, s[44:45] offset:2048
	v_and_b32_e32 v34, 64, v178
	v_add_u32_e32 v34, 64, v34
	v_xor_b32_e32 v35, 32, v178
	v_cmp_lt_i32_e32 vcc, v35, v34
	v_readlane_b32 s6, v253, 39
	v_lshlrev_b32_e32 v128, 1, v33
	v_cndmask_b32_e32 v35, v178, v35, vcc
	v_lshlrev_b32_e32 v38, 2, v35
	v_xor_b32_e32 v35, 16, v178
	v_cmp_lt_i32_e32 vcc, v35, v34
	v_readlane_b32 s7, v253, 40
	s_mov_b64 s[42:43], 0
	v_cndmask_b32_e32 v35, v178, v35, vcc
	v_lshlrev_b32_e32 v39, 2, v35
	v_xor_b32_e32 v35, 8, v178
	v_cmp_lt_i32_e32 vcc, v35, v34
	v_readlane_b32 s48, v254, 45
	v_readlane_b32 s49, v254, 46
	v_cndmask_b32_e32 v35, v178, v35, vcc
	v_lshlrev_b32_e32 v40, 2, v35
	v_xor_b32_e32 v35, 4, v178
	v_cmp_lt_i32_e32 vcc, v35, v34
	v_readlane_b32 s50, v254, 47
	v_readlane_b32 s51, v254, 48
	v_cndmask_b32_e32 v35, v178, v35, vcc
	v_lshlrev_b32_e32 v41, 2, v35
	v_xor_b32_e32 v35, 2, v178
	v_cmp_lt_i32_e32 vcc, v35, v34
	v_readlane_b32 s52, v254, 49
	v_readlane_b32 s53, v254, 50
	v_cndmask_b32_e32 v35, v178, v35, vcc
	v_lshlrev_b32_e32 v42, 2, v35
	v_xor_b32_e32 v35, 1, v178
	v_cmp_lt_i32_e32 vcc, v35, v34
	v_readlane_b32 s54, v254, 51
	v_readlane_b32 s55, v254, 52
	v_cndmask_b32_e32 v34, v178, v35, vcc
	v_lshlrev_b32_e32 v43, 2, v34
	v_lshl_add_u64 v[34:35], s[6:7], 0, v[128:129]
	v_readlane_b32 s56, v254, 53
	v_readlane_b32 s57, v254, 54
	v_readlane_b32 s46, v253, 17
	v_readlane_b32 s47, v253, 18
	v_ashrrev_i32_e32 v249, 31, v32
	v_mov_b32_e32 v248, v32
	v_lshlrev_b64 v[248:249], 11, v[248:249]
	v_lshl_add_u64 v[248:249], v[34:35], 0, v[248:249]
	global_load_dwordx4 v[240:243], v[248:249], off
	global_load_dwordx4 v[244:247], v[248:249], off offset:1024
	s_waitcnt vmcnt(0)
; DI unsigned pack2(float a, float b) { f32x2_t v = {a, b}; return __builtin_bit_cast(unsigned, __builtin_convertvector(v, bf16x2_t)); }
; DI float lo2f(unsigned v) { return __uint_as_float(v << 16); }
; DI float hi2f(unsigned v) { return __uint_as_float(v & 0xffff0000u); }
; DI float wave_sum(float v) { for (int o = 32; o >= 1; o >>= 1) v += __shfl_xor(v, o); return v; }
; DI void ln_phase(int wvs, bf16_t* HB, const float* __restrict__ g, const float* __restrict__ bta, float* fout, bool dostore = true) {
;     ...
;   for (int row = blockIdx.x * 8 + w; row < MTOT; row += gridDim.x * 8) {
;     bf16_t* p = HB + (size_t)row * 1024;
;     float v[16];
;     float s = 0.f;
; #pragma unroll
;     for (int i = 0; i < 2; ++i) {
;       const u32x4 raw = *(const u32x4*)(p + i * 512 + lane * 8);
; #pragma unroll
;       for (int j = 0; j < 4; ++j) { v[i * 8 + 2 * j] = lo2f(raw[j]); v[i * 8 + 2 * j + 1] = hi2f(raw[j]); }
;     }
; #pragma unroll
;     for (int i = 0; i < 16; ++i) s += v[i];
;     const float mean = wave_sum(s) * (1.f / 1024.f);
;     float q = 0.f;
; #pragma unroll
;     for (int i = 0; i < 16; ++i) { v[i] -= mean; q += v[i] * v[i]; }
;     const float rstd = rsqrtf(wave_sum(q) * (1.f / 1024.f) + 1e-5f);
; #pragma unroll
;     for (int i = 0; i < 2; ++i) {
;       const int c = i * 512 + lane * 8;
;       const float4 g0 = *(const float4*)(g + c), g1 = *(const float4*)(g + c + 4), b0 = *(const float4*)(bta + c), b1 = *(const float4*)(bta + c + 4);
;       float o[8];
;       o[0] = v[i * 8 + 0] * rstd * g0.x + b0.x; o[1] = v[i * 8 + 1] * rstd * g0.y + b0.y; o[2] = v[i * 8 + 2] * rstd * g0.z + b0.z; o[3] = v[i * 8 + 3] * rstd * g0.w + b0.w;
;       o[4] = v[i * 8 + 4] * rstd * g1.x + b1.x; o[5] = v[i * 8 + 5] * rstd * g1.y + b1.y; o[6] = v[i * 8 + 6] * rstd * g1.z + b1.z; o[7] = v[i * 8 + 7] * rstd * g1.w + b1.w;
;       if (dostore) {
;         u32x4 pk; pk[0] = pack2(o[0], o[1]); pk[1] = pack2(o[2], o[3]); pk[2] = pack2(o[4], o[5]); pk[3] = pack2(o[6], o[7]);
;         *(u32x4*)(p + c) = pk;
;         if (fout) {
;           *(float4*)(fout + (size_t)row * 1024 + c) = make_float4(o[0], o[1], o[2], o[3]);
;           *(float4*)(fout + (size_t)row * 1024 + c + 4) = make_float4(o[4], o[5], o[6], o[7]);
;         }
;       }
;     }
;   }
.LBB0_499:
	v_ashrrev_i32_e32 v33, 31, v32
	v_lshlrev_b64 v[36:37], 11, v[32:33]
	v_lshl_add_u64 v[36:37], v[34:35], 0, v[36:37]
	s_waitcnt vmcnt(2)
	v_mov_b32_e32 v44, v240
	v_mov_b32_e32 v45, v241
	v_mov_b32_e32 v46, v242
	v_mov_b32_e32 v47, v243
	v_mov_b32_e32 v48, v244
	v_mov_b32_e32 v49, v245
	v_mov_b32_e32 v50, v246
	v_mov_b32_e32 v51, v247
	v_add_u32_e32 v32, s13, v32
	v_ashrrev_i32_e32 v249, 31, v32
	v_mov_b32_e32 v248, v32
	v_lshlrev_b64 v[248:249], 11, v[248:249]
	v_lshl_add_u64 v[248:249], v[34:35], 0, v[248:249]
	global_load_dwordx4 v[240:243], v[248:249], off
	global_load_dwordx4 v[244:247], v[248:249], off offset:1024
	v_lshlrev_b32_e32 v56, 16, v44
	v_and_b32_e32 v57, 0xffff0000, v44
	v_add_f32_e32 v33, 0, v56
	v_lshlrev_b32_e32 v54, 16, v46
	v_and_b32_e32 v55, 0xffff0000, v46
	v_lshlrev_b32_e32 v46, 16, v45
	v_add_f32_e32 v33, v33, v57
	v_lshlrev_b32_e32 v52, 16, v47
	v_and_b32_e32 v53, 0xffff0000, v47
	v_and_b32_e32 v47, 0xffff0000, v45
	v_add_f32_e32 v33, v33, v46
	v_add_f32_e32 v33, v33, v47
	v_add_f32_e32 v33, v33, v54
	v_add_f32_e32 v33, v33, v55
	v_add_f32_e32 v33, v33, v52
	v_add_f32_e32 v33, v33, v53
	v_lshlrev_b32_e32 v60, 16, v48
	v_and_b32_e32 v61, 0xffff0000, v48
	v_add_f32_e32 v33, v33, v60
	v_lshlrev_b32_e32 v58, 16, v50
	v_and_b32_e32 v59, 0xffff0000, v50
	v_lshlrev_b32_e32 v50, 16, v49
	v_add_f32_e32 v33, v33, v61
	v_lshlrev_b32_e32 v44, 16, v51
	v_and_b32_e32 v45, 0xffff0000, v51
	v_and_b32_e32 v51, 0xffff0000, v49
	v_add_f32_e32 v33, v33, v50
	v_add_f32_e32 v33, v33, v51
	v_add_f32_e32 v33, v33, v58
	v_add_f32_e32 v33, v33, v59
	v_add_f32_e32 v33, v33, v44
	v_add_f32_e32 v33, v33, v45
	s_nop 1
	v_add_f32_dpp v33, v33, v33 quad_perm:[1,0,3,2] row_mask:0xf bank_mask:0xf
	s_nop 1
	v_add_f32_dpp v33, v33, v33 quad_perm:[2,3,0,1] row_mask:0xf bank_mask:0xf
	s_nop 1
	v_add_f32_dpp v33, v33, v33 row_half_mirror row_mask:0xf bank_mask:0xf
	s_nop 1
	v_add_f32_dpp v33, v33, v33 row_mirror row_mask:0xf bank_mask:0xf
	v_mov_b32_e32 v48, v33
	s_nop 1
	v_permlane16_swap_b32_e32 v48, v33
	v_add_f32_e32 v33, v33, v48
	v_mov_b32_e32 v48, v33
	s_nop 1
	v_permlane32_swap_b32_e32 v48, v33
	v_add_f32_e32 v33, v33, v48
	v_mul_f32_e32 v48, 0x3a800000, v33
	v_pk_add_f32 v[56:57], v[56:57], v[48:49] op_sel_hi:[1,0] neg_lo:[0,1] neg_hi:[0,1]
	v_pk_add_f32 v[46:47], v[46:47], v[48:49] op_sel_hi:[1,0] neg_lo:[0,1] neg_hi:[0,1]
	v_pk_mul_f32 v[62:63], v[56:57], v[56:57]
	v_pk_mul_f32 v[64:65], v[46:47], v[46:47]
	v_add_f32_e32 v33, v62, v63
	v_pk_add_f32 v[54:55], v[54:55], v[48:49] op_sel_hi:[1,0] neg_lo:[0,1] neg_hi:[0,1]
	v_add_f32_e32 v33, v64, v33
	v_pk_mul_f32 v[66:67], v[54:55], v[54:55]
	v_add_f32_e32 v33, v65, v33
	v_pk_add_f32 v[52:53], v[52:53], v[48:49] op_sel_hi:[1,0] neg_lo:[0,1] neg_hi:[0,1]
	v_add_f32_e32 v33, v66, v33
	v_pk_mul_f32 v[68:69], v[52:53], v[52:53]
	v_add_f32_e32 v33, v67, v33
	v_pk_add_f32 v[60:61], v[60:61], v[48:49] op_sel_hi:[1,0] neg_lo:[0,1] neg_hi:[0,1]
	v_add_f32_e32 v33, v68, v33
	v_pk_mul_f32 v[70:71], v[60:61], v[60:61]
	v_add_f32_e32 v33, v69, v33
	v_pk_add_f32 v[50:51], v[50:51], v[48:49] op_sel_hi:[1,0] neg_lo:[0,1] neg_hi:[0,1]
	v_add_f32_e32 v33, v70, v33
	v_pk_mul_f32 v[72:73], v[50:51], v[50:51]
	v_add_f32_e32 v33, v71, v33
	v_pk_add_f32 v[58:59], v[58:59], v[48:49] op_sel_hi:[1,0] neg_lo:[0,1] neg_hi:[0,1]
	v_add_f32_e32 v33, v72, v33
	v_pk_mul_f32 v[74:75], v[58:59], v[58:59]
	v_add_f32_e32 v33, v73, v33
	v_pk_add_f32 v[48:49], v[44:45], v[48:49] op_sel_hi:[1,0] neg_lo:[0,1] neg_hi:[0,1]
	v_add_f32_e32 v33, v74, v33
	v_pk_mul_f32 v[44:45], v[48:49], v[48:49]
	v_add_f32_e32 v33, v75, v33
	v_add_f32_e32 v33, v44, v33
	v_add_f32_e32 v33, v45, v33
	s_nop 1
	v_add_f32_dpp v33, v33, v33 quad_perm:[1,0,3,2] row_mask:0xf bank_mask:0xf
	s_nop 1
	v_add_f32_dpp v33, v33, v33 quad_perm:[2,3,0,1] row_mask:0xf bank_mask:0xf
	s_nop 1
	v_add_f32_dpp v33, v33, v33 row_half_mirror row_mask:0xf bank_mask:0xf
	s_nop 1
	v_add_f32_dpp v33, v33, v33 row_mirror row_mask:0xf bank_mask:0xf
	v_mov_b32_e32 v44, v33
	s_nop 1
	v_permlane16_swap_b32_e32 v44, v33
	v_add_f32_e32 v33, v33, v44
	v_mov_b32_e32 v44, v33
	s_nop 1
	v_permlane32_swap_b32_e32 v44, v33
	v_add_f32_e32 v33, v33, v44
	v_fmamk_f32 v33, v33, 0x3a800000, v177
	v_cmp_gt_f32_e32 vcc, s75, v33
	v_mul_f32_e32 v44, 0x4b800000, v33
	s_nop 0
	v_cndmask_b32_e32 v33, v33, v44, vcc
	v_rsq_f32_e32 v33, v33
	s_nop 0
	v_mul_f32_e32 v44, 0x45800000, v33
	v_cndmask_b32_e32 v62, v33, v44, vcc
	v_pk_mul_f32 v[44:45], v[56:57], v[62:63] op_sel_hi:[1,0]
	v_pk_mul_f32 v[46:47], v[46:47], v[62:63] op_sel_hi:[1,0]
	v_pk_mul_f32 v[54:55], v[54:55], v[62:63] op_sel_hi:[1,0]
	v_pk_mul_f32 v[52:53], v[52:53], v[62:63] op_sel_hi:[1,0]
	v_pk_fma_f32 v[44:45], v[4:5], v[44:45], v[12:13]
	v_pk_fma_f32 v[46:47], v[6:7], v[46:47], v[14:15]
	v_pk_fma_f32 v[54:55], v[0:1], v[54:55], v[8:9]
	v_pk_fma_f32 v[52:53], v[2:3], v[52:53], v[10:11]
	v_cvt_pk_bf16_f32 v44, v44, v45
	v_cvt_pk_bf16_f32 v45, v46, v47
	v_cvt_pk_bf16_f32 v46, v54, v55
	v_cvt_pk_bf16_f32 v47, v52, v53
	global_store_dwordx4 v[36:37], v[44:47], off
	v_pk_mul_f32 v[48:49], v[48:49], v[62:63] op_sel_hi:[1,0]
	v_cmp_lt_i32_e32 vcc, s76, v32
	v_pk_mul_f32 v[44:45], v[60:61], v[62:63] op_sel_hi:[1,0]
	v_pk_mul_f32 v[46:47], v[50:51], v[62:63] op_sel_hi:[1,0]
	v_pk_mul_f32 v[50:51], v[58:59], v[62:63] op_sel_hi:[1,0]
	v_pk_fma_f32 v[44:45], v[20:21], v[44:45], v[28:29]
	v_pk_fma_f32 v[46:47], v[22:23], v[46:47], v[30:31]
	v_pk_fma_f32 v[50:51], v[16:17], v[50:51], v[24:25]
	v_pk_fma_f32 v[48:49], v[18:19], v[48:49], v[26:27]
	v_cvt_pk_bf16_f32 v44, v44, v45
	v_cvt_pk_bf16_f32 v45, v46, v47
	v_cvt_pk_bf16_f32 v46, v50, v51
	v_cvt_pk_bf16_f32 v47, v48, v49
	s_or_b64 s[42:43], vcc, s[42:43]
	global_store_dwordx4 v[36:37], v[44:47], off offset:1024
	s_andn2_b64 exec, exec, s[42:43]
	s_cbranch_execnz .LBB0_499

; DI float lo2f(unsigned v) { return __uint_as_float(v << 16); }
; DI float hi2f(unsigned v) { return __uint_as_float(v & 0xffff0000u); }
; DI float wave_sum(float v) { for (int o = 32; o >= 1; o >>= 1) v += __shfl_xor(v, o); return v; }
; DI void ln_phase(int wvs, bf16_t* HB, const float* __restrict__ g, const float* __restrict__ bta, float* fout, bool dostore = true) {
;   const int tid = opaque_tid(wvs);
;   const int lane = tid & 63, w = tid >> 6;
;   for (int row = blockIdx.x * 8 + w; row < MTOT; row += gridDim.x * 8) {
;     bf16_t* p = HB + (size_t)row * 1024;
;     float v[16];
;     float s = 0.f;
; #pragma unroll
;     for (int i = 0; i < 2; ++i) {
;       const u32x4 raw = *(const u32x4*)(p + i * 512 + lane * 8);
; #pragma unroll
;       for (int j = 0; j < 4; ++j) { v[i * 8 + 2 * j] = lo2f(raw[j]); v[i * 8 + 2 * j + 1] = hi2f(raw[j]); }
;     }
; #pragma unroll
;     for (int i = 0; i < 16; ++i) s += v[i];
;     const float mean = wave_sum(s) * (1.f / 1024.f);
;     float q = 0.f;
; #pragma unroll
;     for (int i = 0; i < 16; ++i) { v[i] -= mean; q += v[i] * v[i]; }
;     const float rstd = rsqrtf(wave_sum(q) * (1.f / 1024.f) + 1e-5f);
; #pragma unroll
;     for (int i = 0; i < 2; ++i) {
;       const int c = i * 512 + lane * 8;
;       const float4 g0 = *(const float4*)(g + c), g1 = *(const float4*)(g + c + 4), b0 = *(const float4*)(bta + c), b1 = *(const float4*)(bta + c + 4);
.LBB0_1025:
	v_readlane_b32 s6, v251, 2
	v_mbcnt_lo_u32_b32 v0, -1, 0
	v_mbcnt_hi_u32_b32 v0, -1, v0
	s_nop 1
	v_or_b32_e32 v1, s6, v0
	v_ashrrev_i32_e32 v1, 6, v1
	v_readlane_b32 s6, v251, 37
	s_nop 1
	v_add_u32_e32 v32, s6, v1
	s_mov_b32 s6, 0x8000
	v_cmp_gt_i32_e32 vcc, s6, v32
	s_and_saveexec_b64 s[40:41], vcc
	v_readlane_b32 s13, v255, 8
	s_movk_i32 s8, 0x7fff
	s_cbranch_execz .LBB0_1028
	v_lshlrev_b32_e32 v0, 3, v0
	v_and_b32_e32 v33, 0x1f8, v0
	v_readlane_b32 s44, v254, 41
	v_lshlrev_b32_e32 v28, 2, v33
	v_readlane_b32 s48, v254, 45
	v_readlane_b32 s49, v254, 46
	v_readlane_b32 s50, v254, 47
	v_readlane_b32 s51, v254, 48
	s_nop 2
	global_load_dwordx4 v[0:3], v28, s[48:49] offset:16
	s_nop 0
	global_load_dwordx4 v[4:7], v28, s[50:51] offset:16
	global_load_dwordx4 v[8:11], v28, s[48:49]
	global_load_dwordx4 v[12:15], v28, s[50:51]
	global_load_dwordx4 v[16:19], v28, s[48:49] offset:2064
	global_load_dwordx4 v[20:23], v28, s[50:51] offset:2064
	global_load_dwordx4 v[24:27], v28, s[48:49] offset:2048
	s_nop 0
	global_load_dwordx4 v[28:31], v28, s[50:51] offset:2048
	v_and_b32_e32 v34, 64, v178
	v_add_u32_e32 v34, 64, v34
	v_xor_b32_e32 v35, 32, v178
	v_cmp_lt_i32_e32 vcc, v35, v34
	v_readlane_b32 s6, v253, 39
	v_lshlrev_b32_e32 v128, 1, v33
	v_cndmask_b32_e32 v35, v178, v35, vcc
	v_lshlrev_b32_e32 v38, 2, v35
	v_xor_b32_e32 v35, 16, v178
	v_cmp_lt_i32_e32 vcc, v35, v34
	v_readlane_b32 s7, v253, 40
	s_mov_b64 s[42:43], 0
	v_cndmask_b32_e32 v35, v178, v35, vcc
	v_lshlrev_b32_e32 v39, 2, v35
	v_xor_b32_e32 v35, 8, v178
	v_cmp_lt_i32_e32 vcc, v35, v34
	v_readlane_b32 s45, v254, 42
	v_readlane_b32 s46, v254, 43
	v_cndmask_b32_e32 v35, v178, v35, vcc
	v_lshlrev_b32_e32 v40, 2, v35
	v_xor_b32_e32 v35, 4, v178
	v_cmp_lt_i32_e32 vcc, v35, v34
	v_readlane_b32 s47, v254, 44
	v_readlane_b32 s52, v254, 49
	v_cndmask_b32_e32 v35, v178, v35, vcc
	v_lshlrev_b32_e32 v41, 2, v35
	v_xor_b32_e32 v35, 2, v178
	v_cmp_lt_i32_e32 vcc, v35, v34
	v_readlane_b32 s53, v254, 50
	v_readlane_b32 s54, v254, 51
	v_cndmask_b32_e32 v35, v178, v35, vcc
	v_lshlrev_b32_e32 v42, 2, v35
	v_xor_b32_e32 v35, 1, v178
	v_cmp_lt_i32_e32 vcc, v35, v34
	v_readlane_b32 s55, v254, 52
	v_readlane_b32 s56, v254, 53
	v_cndmask_b32_e32 v34, v178, v35, vcc
	v_lshlrev_b32_e32 v43, 2, v34
	v_lshl_add_u64 v[34:35], s[6:7], 0, v[128:129]
	v_readlane_b32 s57, v254, 54
	v_readlane_b32 s58, v254, 55
	v_readlane_b32 s59, v254, 56
	v_ashrrev_i32_e32 v249, 31, v32
	v_mov_b32_e32 v248, v32
	v_lshlrev_b64 v[248:249], 11, v[248:249]
	v_lshl_add_u64 v[248:249], v[34:35], 0, v[248:249]
	global_load_dwordx4 v[240:243], v[248:249], off
	global_load_dwordx4 v[244:247], v[248:249], off offset:1024
	s_waitcnt vmcnt(0)
; DI unsigned pack2(float a, float b) { f32x2_t v = {a, b}; return __builtin_bit_cast(unsigned, __builtin_convertvector(v, bf16x2_t)); }
; DI float lo2f(unsigned v) { return __uint_as_float(v << 16); }
; DI float hi2f(unsigned v) { return __uint_as_float(v & 0xffff0000u); }
; DI float wave_sum(float v) { for (int o = 32; o >= 1; o >>= 1) v += __shfl_xor(v, o); return v; }
; DI void ln_phase(int wvs, bf16_t* HB, const float* __restrict__ g, const float* __restrict__ bta, float* fout, bool dostore = true) {
;     ...
;   for (int row = blockIdx.x * 8 + w; row < MTOT; row += gridDim.x * 8) {
;     bf16_t* p = HB + (size_t)row * 1024;
;     float v[16];
;     float s = 0.f;
; #pragma unroll
;     for (int i = 0; i < 2; ++i) {
;       const u32x4 raw = *(const u32x4*)(p + i * 512 + lane * 8);
; #pragma unroll
;       for (int j = 0; j < 4; ++j) { v[i * 8 + 2 * j] = lo2f(raw[j]); v[i * 8 + 2 * j + 1] = hi2f(raw[j]); }
;     }
; #pragma unroll
;     for (int i = 0; i < 16; ++i) s += v[i];
;     const float mean = wave_sum(s) * (1.f / 1024.f);
;     float q = 0.f;
; #pragma unroll
;     for (int i = 0; i < 16; ++i) { v[i] -= mean; q += v[i] * v[i]; }
;     const float rstd = rsqrtf(wave_sum(q) * (1.f / 1024.f) + 1e-5f);
; #pragma unroll
;     for (int i = 0; i < 2; ++i) {
;       const int c = i * 512 + lane * 8;
;       const float4 g0 = *(const float4*)(g + c), g1 = *(const float4*)(g + c + 4), b0 = *(const float4*)(bta + c), b1 = *(const float4*)(bta + c + 4);
;       float o[8];
;       o[0] = v[i * 8 + 0] * rstd * g0.x + b0.x; o[1] = v[i * 8 + 1] * rstd * g0.y + b0.y; o[2] = v[i * 8 + 2] * rstd * g0.z + b0.z; o[3] = v[i * 8 + 3] * rstd * g0.w + b0.w;
;       o[4] = v[i * 8 + 4] * rstd * g1.x + b1.x; o[5] = v[i * 8 + 5] * rstd * g1.y + b1.y; o[6] = v[i * 8 + 6] * rstd * g1.z + b1.z; o[7] = v[i * 8 + 7] * rstd * g1.w + b1.w;
;       if (dostore) {
;         u32x4 pk; pk[0] = pack2(o[0], o[1]); pk[1] = pack2(o[2], o[3]); pk[2] = pack2(o[4], o[5]); pk[3] = pack2(o[6], o[7]);
;         *(u32x4*)(p + c) = pk;
;         if (fout) {
;           *(float4*)(fout + (size_t)row * 1024 + c) = make_float4(o[0], o[1], o[2], o[3]);
;           *(float4*)(fout + (size_t)row * 1024 + c + 4) = make_float4(o[4], o[5], o[6], o[7]);
;         }
;       }
;     }
;   }
.LBB0_1027:
	v_ashrrev_i32_e32 v33, 31, v32
	v_lshlrev_b64 v[36:37], 11, v[32:33]
	v_lshl_add_u64 v[36:37], v[34:35], 0, v[36:37]
	s_waitcnt vmcnt(2)
	v_mov_b32_e32 v44, v240
	v_mov_b32_e32 v45, v241
	v_mov_b32_e32 v46, v242
	v_mov_b32_e32 v47, v243
	v_mov_b32_e32 v48, v244
	v_mov_b32_e32 v49, v245
	v_mov_b32_e32 v50, v246
	v_mov_b32_e32 v51, v247
	v_add_u32_e32 v32, s13, v32
	v_ashrrev_i32_e32 v249, 31, v32
	v_mov_b32_e32 v248, v32
	v_lshlrev_b64 v[248:249], 11, v[248:249]
	v_lshl_add_u64 v[248:249], v[34:35], 0, v[248:249]
	global_load_dwordx4 v[240:243], v[248:249], off
	global_load_dwordx4 v[244:247], v[248:249], off offset:1024
	v_lshlrev_b32_e32 v56, 16, v44
	v_and_b32_e32 v57, 0xffff0000, v44
	v_add_f32_e32 v33, 0, v56
	v_lshlrev_b32_e32 v54, 16, v46
	v_and_b32_e32 v55, 0xffff0000, v46
	v_lshlrev_b32_e32 v46, 16, v45
	v_add_f32_e32 v33, v33, v57
	v_lshlrev_b32_e32 v52, 16, v47
	v_and_b32_e32 v53, 0xffff0000, v47
	v_and_b32_e32 v47, 0xffff0000, v45
	v_add_f32_e32 v33, v33, v46
	v_add_f32_e32 v33, v33, v47
	v_add_f32_e32 v33, v33, v54
	v_add_f32_e32 v33, v33, v55
	v_add_f32_e32 v33, v33, v52
	v_add_f32_e32 v33, v33, v53
	v_lshlrev_b32_e32 v60, 16, v48
	v_and_b32_e32 v61, 0xffff0000, v48
	v_add_f32_e32 v33, v33, v60
	v_lshlrev_b32_e32 v58, 16, v50
	v_and_b32_e32 v59, 0xffff0000, v50
	v_lshlrev_b32_e32 v50, 16, v49
	v_add_f32_e32 v33, v33, v61
	v_lshlrev_b32_e32 v44, 16, v51
	v_and_b32_e32 v45, 0xffff0000, v51
	v_and_b32_e32 v51, 0xffff0000, v49
	v_add_f32_e32 v33, v33, v50
	v_add_f32_e32 v33, v33, v51
	v_add_f32_e32 v33, v33, v58
	v_add_f32_e32 v33, v33, v59
	v_add_f32_e32 v33, v33, v44
	v_add_f32_e32 v33, v33, v45
	s_nop 1
	v_add_f32_dpp v33, v33, v33 quad_perm:[1,0,3,2] row_mask:0xf bank_mask:0xf
	s_nop 1
	v_add_f32_dpp v33, v33, v33 quad_perm:[2,3,0,1] row_mask:0xf bank_mask:0xf
	s_nop 1
	v_add_f32_dpp v33, v33, v33 row_half_mirror row_mask:0xf bank_mask:0xf
	s_nop 1
	v_add_f32_dpp v33, v33, v33 row_mirror row_mask:0xf bank_mask:0xf
	v_mov_b32_e32 v48, v33
	s_nop 1
	v_permlane16_swap_b32_e32 v48, v33
	v_add_f32_e32 v33, v33, v48
	v_mov_b32_e32 v48, v33
	s_nop 1
	v_permlane32_swap_b32_e32 v48, v33
	v_add_f32_e32 v33, v33, v48
	v_mul_f32_e32 v48, 0x3a800000, v33
	v_pk_add_f32 v[56:57], v[56:57], v[48:49] op_sel_hi:[1,0] neg_lo:[0,1] neg_hi:[0,1]
	v_pk_add_f32 v[46:47], v[46:47], v[48:49] op_sel_hi:[1,0] neg_lo:[0,1] neg_hi:[0,1]
	v_pk_mul_f32 v[62:63], v[56:57], v[56:57]
	v_pk_mul_f32 v[64:65], v[46:47], v[46:47]
	v_add_f32_e32 v33, v62, v63
	v_pk_add_f32 v[54:55], v[54:55], v[48:49] op_sel_hi:[1,0] neg_lo:[0,1] neg_hi:[0,1]
	v_add_f32_e32 v33, v64, v33
	v_pk_mul_f32 v[66:67], v[54:55], v[54:55]
	v_add_f32_e32 v33, v65, v33
	v_pk_add_f32 v[52:53], v[52:53], v[48:49] op_sel_hi:[1,0] neg_lo:[0,1] neg_hi:[0,1]
	v_add_f32_e32 v33, v66, v33
	v_pk_mul_f32 v[68:69], v[52:53], v[52:53]
	v_add_f32_e32 v33, v67, v33
	v_pk_add_f32 v[60:61], v[60:61], v[48:49] op_sel_hi:[1,0] neg_lo:[0,1] neg_hi:[0,1]
	v_add_f32_e32 v33, v68, v33
	v_pk_mul_f32 v[70:71], v[60:61], v[60:61]
	v_add_f32_e32 v33, v69, v33
	v_pk_add_f32 v[50:51], v[50:51], v[48:49] op_sel_hi:[1,0] neg_lo:[0,1] neg_hi:[0,1]
	v_add_f32_e32 v33, v70, v33
	v_pk_mul_f32 v[72:73], v[50:51], v[50:51]
	v_add_f32_e32 v33, v71, v33
	v_pk_add_f32 v[58:59], v[58:59], v[48:49] op_sel_hi:[1,0] neg_lo:[0,1] neg_hi:[0,1]
	v_add_f32_e32 v33, v72, v33
	v_pk_mul_f32 v[74:75], v[58:59], v[58:59]
	v_add_f32_e32 v33, v73, v33
	v_pk_add_f32 v[48:49], v[44:45], v[48:49] op_sel_hi:[1,0] neg_lo:[0,1] neg_hi:[0,1]
	v_add_f32_e32 v33, v74, v33
	v_pk_mul_f32 v[44:45], v[48:49], v[48:49]
	v_add_f32_e32 v33, v75, v33
	v_add_f32_e32 v33, v44, v33
	v_add_f32_e32 v33, v45, v33
	s_nop 1
	v_add_f32_dpp v33, v33, v33 quad_perm:[1,0,3,2] row_mask:0xf bank_mask:0xf
	s_nop 1
	v_add_f32_dpp v33, v33, v33 quad_perm:[2,3,0,1] row_mask:0xf bank_mask:0xf
	s_nop 1
	v_add_f32_dpp v33, v33, v33 row_half_mirror row_mask:0xf bank_mask:0xf
	s_nop 1
	v_add_f32_dpp v33, v33, v33 row_mirror row_mask:0xf bank_mask:0xf
	v_mov_b32_e32 v44, v33
	s_nop 1
	v_permlane16_swap_b32_e32 v44, v33
	v_add_f32_e32 v33, v33, v44
	v_mov_b32_e32 v44, v33
	s_nop 1
	v_permlane32_swap_b32_e32 v44, v33
	v_add_f32_e32 v33, v33, v44
	v_fmamk_f32 v33, v33, 0x3a800000, v177
	v_cmp_gt_f32_e32 vcc, s75, v33
	v_mul_f32_e32 v44, 0x4b800000, v33
	s_nop 0
	v_cndmask_b32_e32 v33, v33, v44, vcc
	v_rsq_f32_e32 v33, v33
	s_nop 0
	v_mul_f32_e32 v44, 0x45800000, v33
	v_cndmask_b32_e32 v62, v33, v44, vcc
	v_pk_mul_f32 v[44:45], v[56:57], v[62:63] op_sel_hi:[1,0]
	v_pk_mul_f32 v[46:47], v[46:47], v[62:63] op_sel_hi:[1,0]
	v_pk_mul_f32 v[54:55], v[54:55], v[62:63] op_sel_hi:[1,0]
	v_pk_mul_f32 v[52:53], v[52:53], v[62:63] op_sel_hi:[1,0]
	v_pk_fma_f32 v[44:45], v[8:9], v[44:45], v[12:13]
	v_pk_fma_f32 v[46:47], v[10:11], v[46:47], v[14:15]
	v_pk_fma_f32 v[54:55], v[0:1], v[54:55], v[4:5]
	v_pk_fma_f32 v[52:53], v[2:3], v[52:53], v[6:7]
	v_cvt_pk_bf16_f32 v44, v44, v45
	v_cvt_pk_bf16_f32 v45, v46, v47
	v_cvt_pk_bf16_f32 v46, v54, v55
	v_cvt_pk_bf16_f32 v47, v52, v53
	global_store_dwordx4 v[36:37], v[44:47], off
	v_pk_mul_f32 v[48:49], v[48:49], v[62:63] op_sel_hi:[1,0]
	v_cmp_lt_i32_e32 vcc, s8, v32
	v_pk_mul_f32 v[44:45], v[60:61], v[62:63] op_sel_hi:[1,0]
	v_pk_mul_f32 v[46:47], v[50:51], v[62:63] op_sel_hi:[1,0]
	v_pk_mul_f32 v[50:51], v[58:59], v[62:63] op_sel_hi:[1,0]
	v_pk_fma_f32 v[44:45], v[24:25], v[44:45], v[28:29]
	v_pk_fma_f32 v[46:47], v[26:27], v[46:47], v[30:31]
	v_pk_fma_f32 v[50:51], v[16:17], v[50:51], v[20:21]
	v_pk_fma_f32 v[48:49], v[18:19], v[48:49], v[22:23]
	v_cvt_pk_bf16_f32 v44, v44, v45
	v_cvt_pk_bf16_f32 v45, v46, v47
	v_cvt_pk_bf16_f32 v46, v50, v51
	v_cvt_pk_bf16_f32 v47, v48, v49
	s_or_b64 s[42:43], vcc, s[42:43]
	global_store_dwordx4 v[36:37], v[44:47], off offset:1024
	s_andn2_b64 exec, exec, s[42:43]
	s_cbranch_execnz .LBB0_1027

; DI float lo2f(unsigned v) { return __uint_as_float(v << 16); }
; DI float hi2f(unsigned v) { return __uint_as_float(v & 0xffff0000u); }
; DI float wave_sum(float v) { for (int o = 32; o >= 1; o >>= 1) v += __shfl_xor(v, o); return v; }
; DI void ln_phase(int wvs, bf16_t* HB, const float* __restrict__ g, const float* __restrict__ bta, float* fout, bool dostore = true) {
;   const int tid = opaque_tid(wvs);
;   const int lane = tid & 63, w = tid >> 6;
;   for (int row = blockIdx.x * 8 + w; row < MTOT; row += gridDim.x * 8) {
;     bf16_t* p = HB + (size_t)row * 1024;
;     float v[16];
;     float s = 0.f;
; #pragma unroll
;     for (int i = 0; i < 2; ++i) {
;       const u32x4 raw = *(const u32x4*)(p + i * 512 + lane * 8);
; #pragma unroll
;       for (int j = 0; j < 4; ++j) { v[i * 8 + 2 * j] = lo2f(raw[j]); v[i * 8 + 2 * j + 1] = hi2f(raw[j]); }
;     }
; #pragma unroll
;     for (int i = 0; i < 16; ++i) s += v[i];
;     const float mean = wave_sum(s) * (1.f / 1024.f);
;     float q = 0.f;
; #pragma unroll
;     for (int i = 0; i < 16; ++i) { v[i] -= mean; q += v[i] * v[i]; }
;     const float rstd = rsqrtf(wave_sum(q) * (1.f / 1024.f) + 1e-5f);
; #pragma unroll
;     for (int i = 0; i < 2; ++i) {
;       const int c = i * 512 + lane * 8;
;       const float4 g0 = *(const float4*)(g + c), g1 = *(const float4*)(g + c + 4), b0 = *(const float4*)(bta + c), b1 = *(const float4*)(bta + c + 4);
.LBB0_1442:
	v_readlane_b32 s6, v251, 2
	v_mbcnt_lo_u32_b32 v0, -1, 0
	v_mbcnt_hi_u32_b32 v0, -1, v0
	s_nop 1
	v_or_b32_e32 v1, s6, v0
	v_ashrrev_i32_e32 v1, 6, v1
	v_readlane_b32 s6, v251, 37
	s_nop 1
	v_add_u32_e32 v40, s6, v1
	s_mov_b32 s6, 0x8000
	v_cmp_gt_i32_e32 vcc, s6, v40
	s_and_saveexec_b64 s[42:43], vcc
	s_cbranch_execz .LBB0_1449
	v_lshlrev_b32_e32 v0, 3, v0
	v_and_b32_e32 v42, 0x1f8, v0
	v_readlane_b32 s44, v254, 17
	v_lshlrev_b32_e32 v28, 2, v42
	v_readlane_b32 s48, v254, 21
	v_readlane_b32 s49, v254, 22
	v_readlane_b32 s50, v254, 23
	v_readlane_b32 s51, v254, 24
	s_nop 2
	global_load_dwordx4 v[0:3], v28, s[48:49] offset:16
	s_nop 0
	global_load_dwordx4 v[4:7], v28, s[50:51] offset:16
	global_load_dwordx4 v[8:11], v28, s[48:49]
	global_load_dwordx4 v[12:15], v28, s[50:51]
	global_load_dwordx4 v[16:19], v28, s[48:49] offset:2064
	global_load_dwordx4 v[20:23], v28, s[50:51] offset:2064
	global_load_dwordx4 v[24:27], v28, s[48:49] offset:2048
	s_nop 0
	global_load_dwordx4 v[28:31], v28, s[50:51] offset:2048
	v_and_b32_e32 v32, 64, v178
	v_add_u32_e32 v32, 64, v32
	v_xor_b32_e32 v33, 32, v178
	v_cmp_lt_i32_e32 vcc, v33, v32
	v_readlane_b32 s6, v253, 39
	v_readlane_b32 s45, v254, 18
	v_cndmask_b32_e32 v33, v178, v33, vcc
	v_lshlrev_b32_e32 v43, 2, v33
	v_xor_b32_e32 v33, 16, v178
	v_cmp_lt_i32_e32 vcc, v33, v32
	v_lshlrev_b32_e32 v128, 1, v42
	v_readlane_b32 s7, v253, 40
	v_cndmask_b32_e32 v33, v178, v33, vcc
	s_waitcnt vmcnt(44)
	v_lshlrev_b32_e32 v60, 2, v33
	v_xor_b32_e32 v33, 8, v178
	v_cmp_lt_i32_e32 vcc, v33, v32
	v_lshl_add_u64 v[44:45], s[6:7], 0, v[128:129]
	s_mov_b64 s[44:45], 0
	v_cndmask_b32_e32 v33, v178, v33, vcc
	v_lshlrev_b32_e32 v61, 2, v33
	v_xor_b32_e32 v33, 4, v178
	v_cmp_lt_i32_e32 vcc, v33, v32
	v_readlane_b32 s46, v254, 19
	v_readlane_b32 s47, v254, 20
	v_cndmask_b32_e32 v33, v178, v33, vcc
	v_lshlrev_b32_e32 v62, 2, v33
	v_xor_b32_e32 v33, 2, v178
	v_cmp_lt_i32_e32 vcc, v33, v32
	s_nop 1
	v_cndmask_b32_e32 v33, v178, v33, vcc
	v_lshlrev_b32_e32 v63, 2, v33
	v_xor_b32_e32 v33, 1, v178
	v_cmp_lt_i32_e32 vcc, v33, v32
	s_nop 1
	v_cndmask_b32_e32 v32, v178, v33, vcc
	v_lshlrev_b32_e32 v64, 2, v32
	v_ashrrev_i32_e32 v249, 31, v40
	v_mov_b32_e32 v248, v40
	v_lshlrev_b64 v[248:249], 11, v[248:249]
	v_lshl_add_u64 v[248:249], v[44:45], 0, v[248:249]
	global_load_dwordx4 v[240:243], v[248:249], off
	global_load_dwordx4 v[244:247], v[248:249], off offset:1024
	s_waitcnt vmcnt(0)
	s_branch .LBB0_1445

; DI unsigned pack2(float a, float b) { f32x2_t v = {a, b}; return __builtin_bit_cast(unsigned, __builtin_convertvector(v, bf16x2_t)); }
; DI float lo2f(unsigned v) { return __uint_as_float(v << 16); }
; DI float hi2f(unsigned v) { return __uint_as_float(v & 0xffff0000u); }
; DI float wave_sum(float v) { for (int o = 32; o >= 1; o >>= 1) v += __shfl_xor(v, o); return v; }
; DI void ln_phase(int wvs, bf16_t* HB, const float* __restrict__ g, const float* __restrict__ bta, float* fout, bool dostore = true) {
;     ...
;   for (int row = blockIdx.x * 8 + w; row < MTOT; row += gridDim.x * 8) {
;     bf16_t* p = HB + (size_t)row * 1024;
;     float v[16];
;     float s = 0.f;
; #pragma unroll
;     for (int i = 0; i < 2; ++i) {
;       const u32x4 raw = *(const u32x4*)(p + i * 512 + lane * 8);
; #pragma unroll
;       for (int j = 0; j < 4; ++j) { v[i * 8 + 2 * j] = lo2f(raw[j]); v[i * 8 + 2 * j + 1] = hi2f(raw[j]); }
;     }
; #pragma unroll
;     for (int i = 0; i < 16; ++i) s += v[i];
;     const float mean = wave_sum(s) * (1.f / 1024.f);
;     float q = 0.f;
; #pragma unroll
;     for (int i = 0; i < 16; ++i) { v[i] -= mean; q += v[i] * v[i]; }
;     const float rstd = rsqrtf(wave_sum(q) * (1.f / 1024.f) + 1e-5f);
; #pragma unroll
;     for (int i = 0; i < 2; ++i) {
;       const int c = i * 512 + lane * 8;
;       const float4 g0 = *(const float4*)(g + c), g1 = *(const float4*)(g + c + 4), b0 = *(const float4*)(bta + c), b1 = *(const float4*)(bta + c + 4);
;       float o[8];
;       o[0] = v[i * 8 + 0] * rstd * g0.x + b0.x; o[1] = v[i * 8 + 1] * rstd * g0.y + b0.y; o[2] = v[i * 8 + 2] * rstd * g0.z + b0.z; o[3] = v[i * 8 + 3] * rstd * g0.w + b0.w;
;       o[4] = v[i * 8 + 4] * rstd * g1.x + b1.x; o[5] = v[i * 8 + 5] * rstd * g1.y + b1.y; o[6] = v[i * 8 + 6] * rstd * g1.z + b1.z; o[7] = v[i * 8 + 7] * rstd * g1.w + b1.w;
;       if (dostore) {
;         u32x4 pk; pk[0] = pack2(o[0], o[1]); pk[1] = pack2(o[2], o[3]); pk[2] = pack2(o[4], o[5]); pk[3] = pack2(o[6], o[7]);
;         *(u32x4*)(p + c) = pk;
;         if (fout) {
;           *(float4*)(fout + (size_t)row * 1024 + c) = make_float4(o[0], o[1], o[2], o[3]);
;           *(float4*)(fout + (size_t)row * 1024 + c + 4) = make_float4(o[4], o[5], o[6], o[7]);
;         }
;       }
.LBB0_1445:
	v_ashrrev_i32_e32 v41, 31, v40
	v_lshlrev_b64 v[32:33], 11, v[40:41]
	v_lshl_add_u64 v[46:47], v[44:45], 0, v[32:33]
	s_waitcnt vmcnt(2)
	v_mov_b32_e32 v32, v240
	v_mov_b32_e32 v33, v241
	v_mov_b32_e32 v34, v242
	v_mov_b32_e32 v35, v243
	v_mov_b32_e32 v36, v244
	v_mov_b32_e32 v37, v245
	v_mov_b32_e32 v38, v246
	v_mov_b32_e32 v39, v247
	v_add_u32_e32 v248, s13, v40
	v_ashrrev_i32_e32 v249, 31, v248
	v_lshlrev_b64 v[248:249], 11, v[248:249]
	v_lshl_add_u64 v[248:249], v[44:45], 0, v[248:249]
	global_load_dwordx4 v[240:243], v[248:249], off
	global_load_dwordx4 v[244:247], v[248:249], off offset:1024
	v_lshlrev_b64 v[48:49], 12, v[40:41]
	v_readlane_b32 s6, v253, 1
	v_readlane_b32 s7, v253, 2
	v_lshl_add_u64 v[48:49], s[10:11], 0, v[48:49]
	v_lshlrev_b32_e32 v128, 2, v42
	v_lshlrev_b32_e32 v52, 16, v32
	v_and_b32_e32 v53, 0xffff0000, v32
	v_add_f32_e32 v32, 0, v52
	v_add_f32_e32 v41, v32, v53
	v_lshlrev_b32_e32 v32, 16, v33
	v_and_b32_e32 v33, 0xffff0000, v33
	v_add_f32_e32 v41, v41, v32
	v_add_f32_e32 v41, v41, v33
	v_lshlrev_b32_e32 v56, 16, v34
	v_and_b32_e32 v57, 0xffff0000, v34
	v_add_f32_e32 v34, v41, v56
	v_add_f32_e32 v41, v34, v57
	v_lshlrev_b32_e32 v34, 16, v35
	v_and_b32_e32 v35, 0xffff0000, v35
	v_add_f32_e32 v41, v41, v34
	v_lshlrev_b32_e32 v50, 16, v36
	v_add_f32_e32 v41, v41, v35
	v_and_b32_e32 v51, 0xffff0000, v36
	v_add_f32_e32 v41, v41, v50
	v_lshlrev_b32_e32 v36, 16, v37
	v_add_f32_e32 v41, v41, v51
	v_and_b32_e32 v37, 0xffff0000, v37
	v_add_f32_e32 v41, v41, v36
	v_lshlrev_b32_e32 v54, 16, v38
	v_add_f32_e32 v41, v41, v37
	v_and_b32_e32 v55, 0xffff0000, v38
	v_add_f32_e32 v41, v41, v54
	v_lshlrev_b32_e32 v38, 16, v39
	v_add_f32_e32 v41, v41, v55
	v_and_b32_e32 v39, 0xffff0000, v39
	v_add_f32_e32 v41, v41, v38
	v_add_f32_e32 v41, v41, v39
	s_nop 1
	v_add_f32_dpp v41, v41, v41 quad_perm:[1,0,3,2] row_mask:0xf bank_mask:0xf
	s_nop 1
	v_add_f32_dpp v41, v41, v41 quad_perm:[2,3,0,1] row_mask:0xf bank_mask:0xf
	s_nop 1
	v_add_f32_dpp v41, v41, v41 row_half_mirror row_mask:0xf bank_mask:0xf
	s_nop 1
	v_add_f32_dpp v41, v41, v41 row_mirror row_mask:0xf bank_mask:0xf
	v_mov_b32_e32 v58, v41
	s_nop 1
	v_permlane16_swap_b32_e32 v58, v41
	v_add_f32_e32 v41, v41, v58
	v_mov_b32_e32 v58, v41
	s_nop 1
	v_permlane32_swap_b32_e32 v58, v41
	v_add_f32_e32 v41, v41, v58
	v_mul_f32_e32 v58, 0x3a800000, v41
	v_pk_add_f32 v[66:67], v[52:53], v[58:59] op_sel_hi:[1,0] neg_lo:[0,1] neg_hi:[0,1]
	v_pk_add_f32 v[32:33], v[32:33], v[58:59] op_sel_hi:[1,0] neg_lo:[0,1] neg_hi:[0,1]
	v_pk_mul_f32 v[68:69], v[66:67], v[66:67]
	v_pk_mul_f32 v[70:71], v[32:33], v[32:33]
	v_add_f32_e32 v41, v68, v69
	v_pk_add_f32 v[72:73], v[56:57], v[58:59] op_sel_hi:[1,0] neg_lo:[0,1] neg_hi:[0,1]
	v_add_f32_e32 v41, v70, v41
	v_pk_mul_f32 v[74:75], v[72:73], v[72:73]
	v_add_f32_e32 v41, v71, v41
	v_pk_add_f32 v[34:35], v[34:35], v[58:59] op_sel_hi:[1,0] neg_lo:[0,1] neg_hi:[0,1]
	v_add_f32_e32 v41, v74, v41
	v_pk_mul_f32 v[76:77], v[34:35], v[34:35]
	v_add_f32_e32 v41, v75, v41
	v_pk_add_f32 v[50:51], v[50:51], v[58:59] op_sel_hi:[1,0] neg_lo:[0,1] neg_hi:[0,1]
	v_add_f32_e32 v41, v76, v41
	v_pk_mul_f32 v[78:79], v[50:51], v[50:51]
	v_add_f32_e32 v41, v77, v41
	v_pk_add_f32 v[52:53], v[36:37], v[58:59] op_sel_hi:[1,0] neg_lo:[0,1] neg_hi:[0,1]
	v_add_f32_e32 v41, v78, v41
	v_pk_mul_f32 v[36:37], v[52:53], v[52:53]
	v_add_f32_e32 v41, v79, v41
	v_pk_add_f32 v[54:55], v[54:55], v[58:59] op_sel_hi:[1,0] neg_lo:[0,1] neg_hi:[0,1]
	v_add_f32_e32 v36, v36, v41
	v_pk_mul_f32 v[80:81], v[54:55], v[54:55]
	v_add_f32_e32 v36, v37, v36
	v_pk_add_f32 v[56:57], v[38:39], v[58:59] op_sel_hi:[1,0] neg_lo:[0,1] neg_hi:[0,1]
	v_add_f32_e32 v36, v80, v36
	v_pk_mul_f32 v[38:39], v[56:57], v[56:57]
	v_add_f32_e32 v36, v81, v36
	v_add_f32_e32 v36, v38, v36
	v_add_f32_e32 v36, v39, v36
	v_cndmask_b32_e64 v41, 0, 1, s[6:7]
	v_cmp_ne_u32_e64 s[40:41], 1, v41
	s_nop 1
	v_add_f32_dpp v36, v36, v36 quad_perm:[1,0,3,2] row_mask:0xf bank_mask:0xf
	s_nop 1
	v_add_f32_dpp v36, v36, v36 quad_perm:[2,3,0,1] row_mask:0xf bank_mask:0xf
	s_nop 1
	v_add_f32_dpp v36, v36, v36 row_half_mirror row_mask:0xf bank_mask:0xf
	s_nop 1
	v_add_f32_dpp v36, v36, v36 row_mirror row_mask:0xf bank_mask:0xf
	v_mov_b32_e32 v37, v36
	s_nop 1
	v_permlane16_swap_b32_e32 v37, v36
	v_add_f32_e32 v36, v36, v37
	v_mov_b32_e32 v37, v36
	s_nop 1
	v_permlane32_swap_b32_e32 v37, v36
	v_add_f32_e32 v36, v36, v37
	v_fmamk_f32 v36, v36, 0x3a800000, v177
	v_cmp_gt_f32_e32 vcc, s75, v36
	v_mul_f32_e32 v37, 0x4b800000, v36
	s_nop 0
	v_cndmask_b32_e32 v36, v36, v37, vcc
	v_rsq_f32_e32 v36, v36
	s_nop 0
	v_mul_f32_e32 v37, 0x45800000, v36
	v_cndmask_b32_e32 v58, v36, v37, vcc
	v_pk_mul_f32 v[32:33], v[32:33], v[58:59] op_sel_hi:[1,0]
	v_pk_mul_f32 v[36:37], v[66:67], v[58:59] op_sel_hi:[1,0]
	v_pk_fma_f32 v[38:39], v[10:11], v[32:33], v[14:15]
	v_pk_mul_f32 v[32:33], v[72:73], v[58:59] op_sel_hi:[1,0]
	v_pk_mul_f32 v[34:35], v[34:35], v[58:59] op_sel_hi:[1,0]
	v_pk_fma_f32 v[36:37], v[8:9], v[36:37], v[12:13]
	v_pk_fma_f32 v[32:33], v[0:1], v[32:33], v[4:5]
	v_pk_fma_f32 v[34:35], v[2:3], v[34:35], v[6:7]
	v_cvt_pk_bf16_f32 v66, v36, v37
	v_cvt_pk_bf16_f32 v67, v38, v39
	v_cvt_pk_bf16_f32 v68, v32, v33
	v_cvt_pk_bf16_f32 v69, v34, v35
	s_andn2_b64 vcc, exec, s[6:7]
	s_cbranch_vccnz .LBB0_1447
	s_nop 0
	v_lshl_add_u64 v[66:67], v[48:49], 0, v[128:129]
	global_store_dwordx4 v[66:67], v[36:39], off
	global_store_dwordx4 v[66:67], v[32:35], off offset:16

; DI float lo2f(unsigned v) { return __uint_as_float(v << 16); }
; DI float hi2f(unsigned v) { return __uint_as_float(v & 0xffff0000u); }
; DI float wave_sum(float v) { for (int o = 32; o >= 1; o >>= 1) v += __shfl_xor(v, o); return v; }
; DI void ln_phase(int wvs, bf16_t* HB, const float* __restrict__ g, const float* __restrict__ bta, float* fout, bool dostore = true) {
;   const int tid = opaque_tid(wvs);
;   const int lane = tid & 63, w = tid >> 6;
;   for (int row = blockIdx.x * 8 + w; row < MTOT; row += gridDim.x * 8) {
;     bf16_t* p = HB + (size_t)row * 1024;
;     float v[16];
;     float s = 0.f;
; #pragma unroll
;     for (int i = 0; i < 2; ++i) {
;       const u32x4 raw = *(const u32x4*)(p + i * 512 + lane * 8);
; #pragma unroll
;       for (int j = 0; j < 4; ++j) { v[i * 8 + 2 * j] = lo2f(raw[j]); v[i * 8 + 2 * j + 1] = hi2f(raw[j]); }
;     }
; #pragma unroll
;     for (int i = 0; i < 16; ++i) s += v[i];
;     const float mean = wave_sum(s) * (1.f / 1024.f);
;     float q = 0.f;
; #pragma unroll
;     for (int i = 0; i < 16; ++i) { v[i] -= mean; q += v[i] * v[i]; }
;     const float rstd = rsqrtf(wave_sum(q) * (1.f / 1024.f) + 1e-5f);
; #pragma unroll
;     for (int i = 0; i < 2; ++i) {
;       const int c = i * 512 + lane * 8;
;       const float4 g0 = *(const float4*)(g + c), g1 = *(const float4*)(g + c + 4), b0 = *(const float4*)(bta + c), b1 = *(const float4*)(bta + c + 4);
.LBB0_1450:
	v_readlane_b32 s6, v251, 2
	v_mbcnt_lo_u32_b32 v0, -1, 0
	v_mbcnt_hi_u32_b32 v0, -1, v0
	s_nop 1
	v_or_b32_e32 v1, s6, v0
	v_ashrrev_i32_e32 v1, 6, v1
	v_readlane_b32 s6, v251, 37
	s_nop 1
	v_add_u32_e32 v32, s6, v1
	s_mov_b32 s6, 0x8000
	v_cmp_gt_i32_e32 vcc, s6, v32
	s_and_saveexec_b64 s[40:41], vcc
	s_movk_i32 s8, 0x7fff
	s_cbranch_execz .LBB0_1453
	v_lshlrev_b32_e32 v0, 3, v0
	v_and_b32_e32 v33, 0x1f8, v0
	v_readlane_b32 s76, v254, 25
	v_lshlrev_b32_e32 v28, 2, v33
	v_readlane_b32 s77, v254, 26
	v_readlane_b32 s78, v254, 27
	v_readlane_b32 s79, v254, 28
	s_nop 2
	global_load_dwordx4 v[0:3], v28, s[76:77] offset:16
	s_nop 0
	global_load_dwordx4 v[4:7], v28, s[78:79] offset:16
	global_load_dwordx4 v[8:11], v28, s[76:77]
	global_load_dwordx4 v[12:15], v28, s[78:79]
	global_load_dwordx4 v[16:19], v28, s[76:77] offset:2064
	global_load_dwordx4 v[20:23], v28, s[78:79] offset:2064
	global_load_dwordx4 v[24:27], v28, s[76:77] offset:2048
	s_nop 0
	global_load_dwordx4 v[28:31], v28, s[78:79] offset:2048
	v_and_b32_e32 v34, 64, v178
	v_add_u32_e32 v34, 64, v34
	v_xor_b32_e32 v35, 32, v178
	v_cmp_lt_i32_e32 vcc, v35, v34
	v_readlane_b32 s6, v253, 39
	v_lshlrev_b32_e32 v128, 1, v33
	v_cndmask_b32_e32 v35, v178, v35, vcc
	v_lshlrev_b32_e32 v38, 2, v35
	v_xor_b32_e32 v35, 16, v178
	v_cmp_lt_i32_e32 vcc, v35, v34
	v_readlane_b32 s7, v253, 40
	s_mov_b64 s[42:43], 0
	v_cndmask_b32_e32 v35, v178, v35, vcc
	v_lshlrev_b32_e32 v39, 2, v35
	v_xor_b32_e32 v35, 8, v178
	v_cmp_lt_i32_e32 vcc, v35, v34
	v_readlane_b32 s80, v254, 29
	v_readlane_b32 s81, v254, 30
	v_cndmask_b32_e32 v35, v178, v35, vcc
	v_lshlrev_b32_e32 v40, 2, v35
	v_xor_b32_e32 v35, 4, v178
	v_cmp_lt_i32_e32 vcc, v35, v34
	v_readlane_b32 s82, v254, 31
	v_readlane_b32 s83, v254, 32
	v_cndmask_b32_e32 v35, v178, v35, vcc
	v_lshlrev_b32_e32 v41, 2, v35
	v_xor_b32_e32 v35, 2, v178
	v_cmp_lt_i32_e32 vcc, v35, v34
	v_readlane_b32 s84, v254, 33
	v_readlane_b32 s85, v254, 34
	v_cndmask_b32_e32 v35, v178, v35, vcc
	v_lshlrev_b32_e32 v42, 2, v35
	v_xor_b32_e32 v35, 1, v178
	v_cmp_lt_i32_e32 vcc, v35, v34
	v_readlane_b32 s86, v254, 35
	v_readlane_b32 s87, v254, 36
	v_cndmask_b32_e32 v34, v178, v35, vcc
	v_lshlrev_b32_e32 v43, 2, v34
	v_lshl_add_u64 v[34:35], s[6:7], 0, v[128:129]
	v_readlane_b32 s88, v254, 37
	v_readlane_b32 s89, v254, 38
	v_readlane_b32 s90, v254, 39
	v_readlane_b32 s91, v254, 40
	v_ashrrev_i32_e32 v249, 31, v32
	v_mov_b32_e32 v248, v32
	v_lshlrev_b64 v[248:249], 11, v[248:249]
	v_lshl_add_u64 v[248:249], v[34:35], 0, v[248:249]
	global_load_dwordx4 v[240:243], v[248:249], off
	global_load_dwordx4 v[244:247], v[248:249], off offset:1024
	s_waitcnt vmcnt(0)
